# dilated attention slow paths also rescale and accumulate in place; copy-out PV blocks removed
# baseline (speedup 1.0000x reference)
;     ...
;     if (first || __any(mx > SM_THR)) {
;         const float d = first ? mx : fmaxf(mx, 0.f), al = __builtin_amdgcn_exp2f(-d);
;         mref += d; l *= al;
; #pragma unroll
;         for (int r = 0; r < 16; ++r) { p0[r] -= d; p1[r] -= d; o0[r] *= al; o1[r] *= al; }
;         if (PRESUB) {
; #pragma unroll
;             for (int r = 0; r < 16; ++r) (*negm)[r] = -mref; }
;     }
.LBB0_756:
	v_mov_b64_e32 v[64:65], v[48:49]
	s_andn2_b64 vcc, exec, s[0:1]
	v_mov_b32_e32 v227, v222
	v_mov_b32_e32 v224, v223
	v_mov_b64_e32 v[62:63], v[46:47]
	v_mov_b64_e32 v[60:61], v[44:45]
	v_mov_b64_e32 v[58:59], v[42:43]
	v_mov_b64_e32 v[56:57], v[40:41]
	v_mov_b64_e32 v[54:55], v[38:39]
	v_mov_b64_e32 v[52:53], v[36:37]
	v_mov_b64_e32 v[50:51], v[34:35]
	s_cbranch_vccnz .LBB0_758
	v_exp_f32_e64 v50, -v172
	v_add_f32_e32 v224, v223, v172
	v_pk_add_f32 v[180:181], v[66:67], v[172:173] op_sel_hi:[1,0] neg_lo:[0,1] neg_hi:[0,1]
	v_pk_add_f32 v[176:177], v[82:83], v[172:173] op_sel_hi:[1,0] neg_lo:[0,1] neg_hi:[0,1]
	v_mul_f32_e32 v227, v222, v50
	v_pk_mul_f32 v[32:33], v[32:33], v[50:51] op_sel_hi:[1,0]
	v_pk_mul_f32 v[30:31], v[30:31], v[50:51] op_sel_hi:[1,0]
	v_pk_mul_f32 v[28:29], v[28:29], v[50:51] op_sel_hi:[1,0]
	v_pk_mul_f32 v[26:27], v[26:27], v[50:51] op_sel_hi:[1,0]
	v_pk_mul_f32 v[24:25], v[24:25], v[50:51] op_sel_hi:[1,0]
	v_pk_mul_f32 v[22:23], v[22:23], v[50:51] op_sel_hi:[1,0]
	v_pk_mul_f32 v[20:21], v[20:21], v[50:51] op_sel_hi:[1,0]
	v_pk_mul_f32 v[18:19], v[18:19], v[50:51] op_sel_hi:[1,0]
	v_pk_mul_f32 v[16:17], v[16:17], v[50:51] op_sel_hi:[1,0]
	v_pk_mul_f32 v[14:15], v[14:15], v[50:51] op_sel_hi:[1,0]
	v_pk_mul_f32 v[12:13], v[12:13], v[50:51] op_sel_hi:[1,0]
	v_pk_mul_f32 v[10:11], v[10:11], v[50:51] op_sel_hi:[1,0]
	v_pk_mul_f32 v[8:9], v[8:9], v[50:51] op_sel_hi:[1,0]
	v_pk_mul_f32 v[6:7], v[6:7], v[50:51] op_sel_hi:[1,0]
	v_pk_mul_f32 v[4:5], v[4:5], v[50:51] op_sel_hi:[1,0]
	v_pk_mul_f32 v[2:3], v[2:3], v[50:51] op_sel_hi:[1,0]
	v_xor_b32_e32 v50, 0x80000000, v224
	v_pk_add_f32 v[188:189], v[68:69], v[172:173] op_sel_hi:[1,0] neg_lo:[0,1] neg_hi:[0,1]
	v_pk_add_f32 v[184:185], v[84:85], v[172:173] op_sel_hi:[1,0] neg_lo:[0,1] neg_hi:[0,1]
	v_pk_add_f32 v[208:209], v[70:71], v[172:173] op_sel_hi:[1,0] neg_lo:[0,1] neg_hi:[0,1]
	v_pk_add_f32 v[204:205], v[86:87], v[172:173] op_sel_hi:[1,0] neg_lo:[0,1] neg_hi:[0,1]
	v_pk_add_f32 v[210:211], v[72:73], v[172:173] op_sel_hi:[1,0] neg_lo:[0,1] neg_hi:[0,1]
	v_pk_add_f32 v[206:207], v[88:89], v[172:173] op_sel_hi:[1,0] neg_lo:[0,1] neg_hi:[0,1]
	v_pk_add_f32 v[192:193], v[74:75], v[172:173] op_sel_hi:[1,0] neg_lo:[0,1] neg_hi:[0,1]
	v_pk_add_f32 v[190:191], v[90:91], v[172:173] op_sel_hi:[1,0] neg_lo:[0,1] neg_hi:[0,1]
	v_pk_add_f32 v[186:187], v[76:77], v[172:173] op_sel_hi:[1,0] neg_lo:[0,1] neg_hi:[0,1]
	v_pk_add_f32 v[182:183], v[92:93], v[172:173] op_sel_hi:[1,0] neg_lo:[0,1] neg_hi:[0,1]
	v_pk_add_f32 v[178:179], v[78:79], v[172:173] op_sel_hi:[1,0] neg_lo:[0,1] neg_hi:[0,1]
	v_pk_add_f32 v[174:175], v[94:95], v[172:173] op_sel_hi:[1,0] neg_lo:[0,1] neg_hi:[0,1]
	v_pk_add_f32 v[170:171], v[80:81], v[172:173] op_sel_hi:[1,0] neg_lo:[0,1] neg_hi:[0,1]
	v_pk_add_f32 v[168:169], v[96:97], v[172:173] op_sel_hi:[1,0] neg_lo:[0,1] neg_hi:[0,1]
	v_mov_b32_e32 v51, v50
	v_mov_b32_e32 v52, v50
	v_mov_b32_e32 v53, v50
	v_mov_b32_e32 v54, v50
	v_mov_b32_e32 v55, v50
	v_mov_b32_e32 v56, v50
	v_mov_b32_e32 v57, v50
	v_mov_b32_e32 v58, v50
	v_mov_b32_e32 v59, v50
	v_mov_b32_e32 v60, v50
	v_mov_b32_e32 v61, v50
	v_mov_b32_e32 v62, v50
	v_mov_b32_e32 v63, v50
	v_mov_b32_e32 v64, v50
	v_mov_b32_e32 v65, v50

; #define LAS __attribute__((address_space(3)))
; __device__ __forceinline__ float xhalf_max(float v) { auto rr = __builtin_amdgcn_permlane32_swap(__float_as_uint(v), __float_as_uint(v), false, false); return fmaxf(__uint_as_float(rr[0]), __uint_as_float(rr[1])); }
;     ...
;     float mx = fmaxf(fmaxf(p0[0], p1[0]), fmaxf(p0[1], p1[1]));
; #pragma unroll
;     for (int r = 2; r < 16; r += 2) { mx = fmaxf(fmaxf(mx, p0[r]), p1[r]); mx = fmaxf(fmaxf(mx, p0[r + 1]), p1[r + 1]); }
;     mx = xhalf_max(mx);
;     if (first || __any(mx > SM_THR)) {
; template <int MODE> __device__ __forceinline__ void attn_unit(LAS unsigned char* lds, const AttnP& P, int b, int h, int qb) {
;     ...
;                 else { const int dmin = q0w - (64 * t + 63), dmax = q0w + 31 - 64 * t;
;                     const bool nearb = (dmin >= 0 && dmax <= 128), midb = (dmin > 128 && dmax <= 512), farb = (dmin > 512 && dmax <= 2048);
;                     if (nearb || midb || farb) { f32x16 wm; const LAS f32x4* wp = wml + (nearb ? 0 : (midb ? 256 : 512));
; #pragma unroll
;                         for (int i = 0; i < 4; ++i) { const f32x4 w = wp[i];
; #pragma unroll
;                             for (int j = 0; j < 4; ++j) wm[4 * i + j] = w[j]; }
;                         softmax_step<1, true>(p0, p1, m1, l1, oa0, oa1, first, wm, dlt0, 0.f, &negm1); }
.LBB0_759:
	s_and_b64 vcc, exec, s[0:1]
	s_cbranch_vccz dilpv_fast1
	v_max_f32_e32 v98, v226, v225
	v_max3_f32 v98, v66, v82, v98
	v_max3_f32 v98, v98, v68, v84
	v_max3_f32 v98, v98, v69, v85
	v_max3_f32 v98, v98, v70, v86
	v_max3_f32 v98, v98, v71, v87
	v_max3_f32 v98, v98, v72, v88
	v_max3_f32 v98, v98, v73, v89
	s_and_b64 s[0:1], s[38:39], exec
	v_max3_f32 v98, v98, v74, v90
	s_movk_i32 s0, 0x100
	v_max3_f32 v98, v98, v75, v91
	s_cselect_b32 s3, s0, 0x200
	s_and_b64 s[0:1], s[26:27], exec
	v_max3_f32 v98, v98, v76, v92
	s_cselect_b32 s0, 0, s3
	v_max3_f32 v98, v98, v77, v93
	v_lshl_add_u32 v50, s0, 4, v214
	v_max3_f32 v98, v98, v78, v94
	ds_read_b128 v[62:65], v50
	ds_read_b128 v[58:61], v50 offset:16
	ds_read_b128 v[54:57], v50 offset:32
	ds_read_b128 v[50:53], v50 offset:48
	v_max3_f32 v98, v98, v79, v95
	v_max3_f32 v98, v98, v80, v96
	v_max3_f32 v98, v98, v81, v97
	v_mov_b32_e32 v99, v98
	s_nop 1
	v_permlane32_swap_b32_e32 v98, v99
	v_max_f32_e32 v99, v99, v99
	v_max_f32_e32 v98, v98, v98
	v_max_f32_e32 v99, v98, v99
	s_and_b64 vcc, exec, s[20:21]
	s_cbranch_vccz .LBB0_776
	v_cmp_lt_f32_e32 vcc, s37, v99
	s_mov_b64 s[4:5], 0
	s_mov_b64 s[0:1], 0
	s_cbranch_vccz .LBB0_763
	v_max_f32_e32 v98, v99, v99
	v_max_f32_e32 v98, 0, v98
	s_mov_b64 s[0:1], -1

; #define LAS __attribute__((address_space(3)))
; #define MFMA32(a, b, c) __builtin_amdgcn_mfma_f32_32x32x16_bf16((a), (b), (c), 0, 0, 0)
; template <int MODE> __device__ __forceinline__ void attn_unit(LAS unsigned char* lds, const AttnP& P, int b, int h, int qb) {
;     ...
;     auto pv = [&](const int voff) __attribute__((always_inline)) {
;         const LAS unsigned char* vb_ = lds + L_V + voff + r32 * VROWB + hi * 16;
; #pragma unroll
;         for (int j = 0; j < 4; ++j) { const bf16x8 v0 = *(const LAS bf16x8*)(vb_ + j * 32), v1 = *(const LAS bf16x8*)(vb_ + 32 * VROWB + j * 32);
;             oa0 = MFMA32(v0, pa[j], oa0); oa1 = MFMA32(v1, pa[j], oa1);
;             if (MODE == 1) { ob0 = MFMA32(v0, pb[j], ob0); ob1 = MFMA32(v1, pb[j], ob1); } }
;     };
dilpv_fast1:
	s_mul_i32 s0, s16, 0x4400
	v_add_u32_e32 v106, s0, v221
	ds_read_b128 v[98:101], v106 offset:36864
	ds_read_b128 v[232:235], v106 offset:45568
	ds_read_b128 v[236:239], v106 offset:36896
	v_cvt_pk_bf16_f32 v102, v173, v177
	v_cvt_pk_bf16_f32 v103, v181, v185
	v_cvt_pk_bf16_f32 v104, v189, v205
	v_cvt_pk_bf16_f32 v105, v209, v207
	v_add_f32_e32 v222, v227, v170
	s_mov_b64 s[0:1], 0
	s_waitcnt lgkmcnt(2)
	v_mfma_f32_32x32x16_bf16 v[18:33], v[98:101], v[102:105], v[18:33]
	ds_read_b128 v[98:101], v106 offset:45600
	s_waitcnt lgkmcnt(2)
	v_mfma_f32_32x32x16_bf16 v[2:17], v[232:235], v[102:105], v[2:17]
	ds_read_b128 v[232:235], v106 offset:36928
	v_cvt_pk_bf16_f32 v102, v211, v191
	v_cvt_pk_bf16_f32 v103, v193, v183
	v_cvt_pk_bf16_f32 v104, v187, v175
	v_cvt_pk_bf16_f32 v105, v179, v169
	s_nop 0
	s_waitcnt lgkmcnt(2)
	v_mfma_f32_32x32x16_bf16 v[18:33], v[236:239], v[102:105], v[18:33]
	ds_read_b128 v[236:239], v106 offset:45632
	s_waitcnt lgkmcnt(2)
	v_mfma_f32_32x32x16_bf16 v[2:17], v[98:101], v[102:105], v[2:17]
	ds_read_b128 v[98:101], v106 offset:36960
	v_cvt_pk_bf16_f32 v102, v172, v176
	v_cvt_pk_bf16_f32 v103, v180, v184
	v_cvt_pk_bf16_f32 v104, v188, v204
	v_cvt_pk_bf16_f32 v105, v208, v206
	s_nop 0
	s_waitcnt lgkmcnt(2)
	v_mfma_f32_32x32x16_bf16 v[18:33], v[232:235], v[102:105], v[18:33]
	ds_read_b128 v[232:235], v106 offset:45664
	s_waitcnt lgkmcnt(2)
	v_mfma_f32_32x32x16_bf16 v[2:17], v[236:239], v[102:105], v[2:17]
	v_cvt_pk_bf16_f32 v102, v210, v190
	v_cvt_pk_bf16_f32 v103, v192, v182
	v_cvt_pk_bf16_f32 v104, v186, v174
	v_cvt_pk_bf16_f32 v105, v178, v168
	s_nop 0
	s_waitcnt lgkmcnt(1)
	v_mfma_f32_32x32x16_bf16 v[18:33], v[98:101], v[102:105], v[18:33]
	s_waitcnt lgkmcnt(0)
	v_mfma_f32_32x32x16_bf16 v[2:17], v[232:235], v[102:105], v[2:17]
	s_nop 15
	s_nop 3

;     ...
;     if (first || __any(mx > SM_THR)) {
;         const float d = first ? mx : fmaxf(mx, 0.f), al = __builtin_amdgcn_exp2f(-d);
;         mref += d; l *= al;
; #pragma unroll
;         for (int r = 0; r < 16; ++r) { p0[r] -= d; p1[r] -= d; o0[r] *= al; o1[r] *= al; }
;         if (PRESUB) {
; #pragma unroll
;             for (int r = 0; r < 16; ++r) (*negm)[r] = -mref; }
;     }
.LBB0_779:
	v_mov_b64_e32 v[34:35], v[50:51]
	s_andn2_b64 vcc, exec, s[0:1]
	v_mov_b32_e32 v227, v222
	v_mov_b32_e32 v223, v224
	v_mov_b64_e32 v[36:37], v[52:53]
	v_mov_b64_e32 v[38:39], v[54:55]
	v_mov_b64_e32 v[40:41], v[56:57]
	v_mov_b64_e32 v[42:43], v[58:59]
	v_mov_b64_e32 v[44:45], v[60:61]
	v_mov_b64_e32 v[46:47], v[62:63]
	v_mov_b64_e32 v[48:49], v[64:65]
	s_cbranch_vccnz .LBB0_781
	v_exp_f32_e64 v34, -v172
	v_add_f32_e32 v223, v224, v172
	v_pk_add_f32 v[180:181], v[66:67], v[172:173] op_sel_hi:[1,0] neg_lo:[0,1] neg_hi:[0,1]
	v_pk_add_f32 v[176:177], v[82:83], v[172:173] op_sel_hi:[1,0] neg_lo:[0,1] neg_hi:[0,1]
	v_mul_f32_e32 v227, v222, v34
	v_pk_mul_f32 v[32:33], v[32:33], v[34:35] op_sel_hi:[1,0]
	v_pk_mul_f32 v[30:31], v[30:31], v[34:35] op_sel_hi:[1,0]
	v_pk_mul_f32 v[28:29], v[28:29], v[34:35] op_sel_hi:[1,0]
	v_pk_mul_f32 v[26:27], v[26:27], v[34:35] op_sel_hi:[1,0]
	v_pk_mul_f32 v[24:25], v[24:25], v[34:35] op_sel_hi:[1,0]
	v_pk_mul_f32 v[22:23], v[22:23], v[34:35] op_sel_hi:[1,0]
	v_pk_mul_f32 v[20:21], v[20:21], v[34:35] op_sel_hi:[1,0]
	v_pk_mul_f32 v[18:19], v[18:19], v[34:35] op_sel_hi:[1,0]
	v_pk_mul_f32 v[16:17], v[16:17], v[34:35] op_sel_hi:[1,0]
	v_pk_mul_f32 v[14:15], v[14:15], v[34:35] op_sel_hi:[1,0]
	v_pk_mul_f32 v[12:13], v[12:13], v[34:35] op_sel_hi:[1,0]
	v_pk_mul_f32 v[10:11], v[10:11], v[34:35] op_sel_hi:[1,0]
	v_pk_mul_f32 v[8:9], v[8:9], v[34:35] op_sel_hi:[1,0]
	v_pk_mul_f32 v[6:7], v[6:7], v[34:35] op_sel_hi:[1,0]
	v_pk_mul_f32 v[4:5], v[4:5], v[34:35] op_sel_hi:[1,0]
	v_pk_mul_f32 v[2:3], v[2:3], v[34:35] op_sel_hi:[1,0]
	v_xor_b32_e32 v34, 0x80000000, v223
	v_pk_add_f32 v[188:189], v[68:69], v[172:173] op_sel_hi:[1,0] neg_lo:[0,1] neg_hi:[0,1]
	v_pk_add_f32 v[184:185], v[84:85], v[172:173] op_sel_hi:[1,0] neg_lo:[0,1] neg_hi:[0,1]
	v_pk_add_f32 v[208:209], v[70:71], v[172:173] op_sel_hi:[1,0] neg_lo:[0,1] neg_hi:[0,1]
	v_pk_add_f32 v[204:205], v[86:87], v[172:173] op_sel_hi:[1,0] neg_lo:[0,1] neg_hi:[0,1]
	v_pk_add_f32 v[210:211], v[72:73], v[172:173] op_sel_hi:[1,0] neg_lo:[0,1] neg_hi:[0,1]
	v_pk_add_f32 v[206:207], v[88:89], v[172:173] op_sel_hi:[1,0] neg_lo:[0,1] neg_hi:[0,1]
	v_pk_add_f32 v[192:193], v[74:75], v[172:173] op_sel_hi:[1,0] neg_lo:[0,1] neg_hi:[0,1]
	v_pk_add_f32 v[190:191], v[90:91], v[172:173] op_sel_hi:[1,0] neg_lo:[0,1] neg_hi:[0,1]
	v_pk_add_f32 v[186:187], v[76:77], v[172:173] op_sel_hi:[1,0] neg_lo:[0,1] neg_hi:[0,1]
	v_pk_add_f32 v[182:183], v[92:93], v[172:173] op_sel_hi:[1,0] neg_lo:[0,1] neg_hi:[0,1]
	v_pk_add_f32 v[178:179], v[78:79], v[172:173] op_sel_hi:[1,0] neg_lo:[0,1] neg_hi:[0,1]
	v_pk_add_f32 v[174:175], v[94:95], v[172:173] op_sel_hi:[1,0] neg_lo:[0,1] neg_hi:[0,1]
	v_pk_add_f32 v[170:171], v[80:81], v[172:173] op_sel_hi:[1,0] neg_lo:[0,1] neg_hi:[0,1]
	v_pk_add_f32 v[168:169], v[96:97], v[172:173] op_sel_hi:[1,0] neg_lo:[0,1] neg_hi:[0,1]
	v_mov_b32_e32 v35, v34
	v_mov_b32_e32 v36, v34
	v_mov_b32_e32 v37, v34
	v_mov_b32_e32 v38, v34
	v_mov_b32_e32 v39, v34
	v_mov_b32_e32 v40, v34
	v_mov_b32_e32 v41, v34
	v_mov_b32_e32 v42, v34
	v_mov_b32_e32 v43, v34
	v_mov_b32_e32 v44, v34
	v_mov_b32_e32 v45, v34
	v_mov_b32_e32 v46, v34
	v_mov_b32_e32 v47, v34
	v_mov_b32_e32 v48, v34
	v_mov_b32_e32 v49, v34

; #define LAS __attribute__((address_space(3)))
; __device__ __forceinline__ float xhalf_max(float v) { auto rr = __builtin_amdgcn_permlane32_swap(__float_as_uint(v), __float_as_uint(v), false, false); return fmaxf(__uint_as_float(rr[0]), __uint_as_float(rr[1])); }
;     ...
;     float mx = fmaxf(fmaxf(p0[0], p1[0]), fmaxf(p0[1], p1[1]));
; #pragma unroll
;     for (int r = 2; r < 16; r += 2) { mx = fmaxf(fmaxf(mx, p0[r]), p1[r]); mx = fmaxf(fmaxf(mx, p0[r + 1]), p1[r + 1]); }
;     mx = xhalf_max(mx);
;     if (first || __any(mx > SM_THR)) {
; template <int MODE> __device__ __forceinline__ void attn_unit(LAS unsigned char* lds, const AttnP& P, int b, int h, int qb) {
;     ...
;                 else { const int dmin = q0w - (64 * t + 63), dmax = q0w + 31 - 64 * t;
;                     const bool nearb = (dmin >= 0 && dmax <= 128), midb = (dmin > 128 && dmax <= 512), farb = (dmin > 512 && dmax <= 2048);
;                     if (nearb || midb || farb) { f32x16 wm; const LAS f32x4* wp = wml + (nearb ? 0 : (midb ? 256 : 512));
; #pragma unroll
;                         for (int i = 0; i < 4; ++i) { const f32x4 w = wp[i];
; #pragma unroll
;                             for (int j = 0; j < 4; ++j) wm[4 * i + j] = w[j]; }
;                         softmax_step<1, true>(p0, p1, m1, l1, oa0, oa1, first, wm, dlt0, 0.f, &negm1); }
.LBB0_782:
	s_and_b64 vcc, exec, s[0:1]
	s_cbranch_vccz dilpv_fast2
	v_max_f32_e32 v98, v226, v225
	v_max3_f32 v98, v66, v82, v98
	v_max3_f32 v98, v98, v68, v84
	v_max3_f32 v98, v98, v69, v85
	v_max3_f32 v98, v98, v70, v86
	v_max3_f32 v98, v98, v71, v87
	v_max3_f32 v98, v98, v72, v88
	v_max3_f32 v98, v98, v73, v89
	s_and_b64 s[0:1], s[26:27], exec
	v_max3_f32 v98, v98, v74, v90
	s_movk_i32 s0, 0x100
	v_max3_f32 v98, v98, v75, v91
	s_cselect_b32 s3, s0, 0x200
	s_and_b64 s[0:1], s[8:9], exec
	v_max3_f32 v98, v98, v76, v92
	s_cselect_b32 s0, 0, s3
	v_max3_f32 v98, v98, v77, v93
	v_lshl_add_u32 v34, s0, 4, v214
	v_max3_f32 v98, v98, v78, v94
	ds_read_b128 v[46:49], v34
	ds_read_b128 v[42:45], v34 offset:16
	ds_read_b128 v[38:41], v34 offset:32
	ds_read_b128 v[34:37], v34 offset:48
	v_max3_f32 v98, v98, v79, v95
	v_max3_f32 v98, v98, v80, v96
	v_max3_f32 v98, v98, v81, v97
	v_mov_b32_e32 v99, v98
	s_nop 1
	v_permlane32_swap_b32_e32 v98, v99
	v_max_f32_e32 v99, v99, v99
	v_max_f32_e32 v98, v98, v98
	v_max_f32_e32 v99, v98, v99
	s_and_b64 vcc, exec, s[20:21]
	s_cbranch_vccz .LBB0_793
	v_cmp_lt_f32_e32 vcc, s37, v99
	s_mov_b64 s[4:5], 0
	s_mov_b64 s[0:1], 0
	s_cbranch_vccz .LBB0_786
	v_max_f32_e32 v98, v99, v99
	v_max_f32_e32 v98, 0, v98
	s_mov_b64 s[0:1], -1

; #define LAS __attribute__((address_space(3)))
; #define MFMA32(a, b, c) __builtin_amdgcn_mfma_f32_32x32x16_bf16((a), (b), (c), 0, 0, 0)
; template <int MODE> __device__ __forceinline__ void attn_unit(LAS unsigned char* lds, const AttnP& P, int b, int h, int qb) {
;     ...
;     auto pv = [&](const int voff) __attribute__((always_inline)) {
;         const LAS unsigned char* vb_ = lds + L_V + voff + r32 * VROWB + hi * 16;
; #pragma unroll
;         for (int j = 0; j < 4; ++j) { const bf16x8 v0 = *(const LAS bf16x8*)(vb_ + j * 32), v1 = *(const LAS bf16x8*)(vb_ + 32 * VROWB + j * 32);
;             oa0 = MFMA32(v0, pa[j], oa0); oa1 = MFMA32(v1, pa[j], oa1);
;             if (MODE == 1) { ob0 = MFMA32(v0, pb[j], ob0); ob1 = MFMA32(v1, pb[j], ob1); } }
;     };
dilpv_fast2:
	s_lshl_b32 s0, s16, 10
	s_sub_i32 s0, s2, s0
	v_add3_u32 v106, s0, v220, v0
	ds_read_b128 v[98:101], v106 offset:36992
	ds_read_b128 v[232:235], v106 offset:45696
	ds_read_b128 v[236:239], v106 offset:37024
	v_cvt_pk_bf16_f32 v102, v173, v177
	v_cvt_pk_bf16_f32 v103, v181, v185
	v_cvt_pk_bf16_f32 v104, v189, v205
	v_cvt_pk_bf16_f32 v105, v209, v207
	v_add_f32_e32 v222, v227, v170
	s_mov_b64 s[0:1], 0
	s_waitcnt lgkmcnt(2)
	v_mfma_f32_32x32x16_bf16 v[18:33], v[98:101], v[102:105], v[18:33]
	ds_read_b128 v[98:101], v106 offset:45728
	s_waitcnt lgkmcnt(2)
	v_mfma_f32_32x32x16_bf16 v[2:17], v[232:235], v[102:105], v[2:17]
	ds_read_b128 v[232:235], v106 offset:37056
	v_cvt_pk_bf16_f32 v102, v211, v191
	v_cvt_pk_bf16_f32 v103, v193, v183
	v_cvt_pk_bf16_f32 v104, v187, v175
	v_cvt_pk_bf16_f32 v105, v179, v169
	s_nop 0
	s_waitcnt lgkmcnt(2)
	v_mfma_f32_32x32x16_bf16 v[18:33], v[236:239], v[102:105], v[18:33]
	ds_read_b128 v[236:239], v106 offset:45760
	s_waitcnt lgkmcnt(2)
	v_mfma_f32_32x32x16_bf16 v[2:17], v[98:101], v[102:105], v[2:17]
	ds_read_b128 v[98:101], v106 offset:37088
	v_cvt_pk_bf16_f32 v102, v172, v176
	v_cvt_pk_bf16_f32 v103, v180, v184
	v_cvt_pk_bf16_f32 v104, v188, v204
	v_cvt_pk_bf16_f32 v105, v208, v206
	s_nop 0
	s_waitcnt lgkmcnt(2)
	v_mfma_f32_32x32x16_bf16 v[18:33], v[232:235], v[102:105], v[18:33]
	ds_read_b128 v[232:235], v106 offset:45792
	s_waitcnt lgkmcnt(2)
	v_mfma_f32_32x32x16_bf16 v[2:17], v[236:239], v[102:105], v[2:17]
	v_cvt_pk_bf16_f32 v102, v210, v190
	v_cvt_pk_bf16_f32 v103, v192, v182
	v_cvt_pk_bf16_f32 v104, v186, v174
	v_cvt_pk_bf16_f32 v105, v178, v168
	s_nop 0
	s_waitcnt lgkmcnt(1)
	v_mfma_f32_32x32x16_bf16 v[18:33], v[98:101], v[102:105], v[18:33]
	s_waitcnt lgkmcnt(0)
	v_mfma_f32_32x32x16_bf16 v[2:17], v[232:235], v[102:105], v[2:17]
	s_nop 15
	s_nop 3
